# attention-B final pass rewritten by hand: 8 gate loads issued together behind counted vmcnt(7) waits instead of load+vmcnt(0) per item (on top of no-setprio GEMM loops + batched prologue weight loads)
# speedup vs baseline: 1.0343x; 1.0092x over previous
; #define LAS __attribute__((address_space(3)))
; template <int MIX, bool DRY = false>
; __device__ __forceinline__ void attn_phase(LAS unsigned char* lds, const bf16_t* Qb, const bf16_t* Kb, const bf16_t* Vb, bf16_t* Gb, const float* qg, const float* kg, const float* sinks) {
;     ...
;             const bool more = unit + (int)gridDim.x < NUNITS;
;             STAGE_LOAD(more ? unit + (int)gridDim.x : unit, 0)
; #pragma unroll 4
;             for (int it = 0; it < (DRY ? 0 : 8); ++it) {
;                 const int item = it * 512 + tidu, row = item >> 3, dg = item & 7, hr = row / CT, tl = row % CT;
;                 const int f = ((tl >> 1) ^ (tl >> 4) ^ (hr << 2)) & 15, head = kvh * REP + hr;
;                 const LAS unsigned char* orow = Oacc + row * 128;
;                 const u32x2 o0 = *(const LAS u32x2*)(orow + (((2 * dg) ^ f) << 3)), o1 = *(const LAS u32x2*)(orow + (((2 * dg + 1) ^ f) << 3));
;                 const float inv = 1.0f / lacc[row];
;                 u32x4* gp = (u32x4*)(Gb + (rowb + t0 + tl) * 1024 + head * 64 + 8 * dg);
;                 const u32x4 gv = *gp;
.LBB0_469:
	v_readlane_b32 s7, v250, 1
	s_add_i32 s6, s7, s80
	s_cmpk_lt_i32 s6, 0x400
	s_cselect_b64 s[0:1], -1, 0
	s_and_b64 s[4:5], s[0:1], exec
	s_cselect_b32 s7, s6, s7
	s_ashr_i32 s4, s7, 3
	s_andn2_b32 s4, s4, 31
	v_readlane_b32 s5, v250, 5
	s_add_i32 s4, s4, s5
	v_readlane_b32 s5, v250, 4
	s_or_b32 s8, s5, s4
	v_readlane_b32 s4, v253, 39
	v_readlane_b32 s5, v253, 40
	s_and_b64 s[4:5], s[4:5], exec
	s_cselect_b32 s4, s8, s7
	s_ashr_i32 s5, s4, 31
	s_lshr_b32 s7, s5, 27
	s_add_i32 s7, s4, s7
	s_ashr_i32 s8, s7, 5
	s_lshr_b32 s9, s8, 30
	s_add_i32 s9, s8, s9
	s_and_b32 s9, s9, 0x3fffffc
	s_and_b32 s7, s7, 0x1ffffe0
	s_sub_i32 s8, s8, s9
	s_lshr_b32 s5, s5, 25
	s_sub_i32 s7, s4, s7
	s_add_i32 s4, s4, s5
	s_lshl_b32 s8, s8, 6
	s_ashr_i32 s4, s4, 7
	s_ashr_i32 s9, s8, 31
	s_lshl_b32 s7, s7, 7
	s_ashr_i32 s5, s4, 31
	s_lshl_b64 s[8:9], s[8:9], 1
	v_readlane_b32 s10, v253, 56
	v_readlane_b32 s11, v253, 57
	s_add_u32 s10, s10, s8
	s_addc_u32 s11, s11, s9
	v_readlane_b32 s12, v253, 60
	v_mov_b32_e32 v16, v202
	s_waitcnt lgkmcnt(0)
	s_barrier
	v_readlane_b32 s13, v253, 61
	s_add_u32 s8, s12, s8
	s_addc_u32 s9, s13, s9
	v_ashrrev_i32_e32 v24, 3, v16
	s_add_i32 s12, s7, 0xffffff80
	v_min_i32_e32 v20, 0xff, v24
	v_add_u32_e32 v20, s12, v20
	v_ashrrev_i32_e32 v21, 31, v20
	s_lshl_b64 s[4:5], s[4:5], 20
	v_lshlrev_b32_e32 v16, 4, v16
	v_lshlrev_b64 v[20:21], 8, v[20:21]
	v_and_b32_e32 v112, 0x70, v16
	v_lshl_add_u64 v[20:21], v[20:21], 0, s[4:5]
	v_lshl_add_u64 v[16:17], s[10:11], 0, v[112:113]
	v_lshl_add_u64 v[18:19], s[8:9], 0, v[112:113]
	v_lshlrev_b64 v[20:21], 1, v[20:21]
	v_lshl_add_u64 v[22:23], v[16:17], 0, v[20:21]
	v_lshl_add_u64 v[20:21], v[18:19], 0, v[20:21]
	global_load_dwordx4 v[114:117], v[22:23], off
	global_load_dwordx4 v[118:121], v[20:21], off
	v_min_i32_e32 v20, 0xbf, v24
	s_sub_i32 s8, s7, 64
	v_add_u32_e32 v20, s8, v20
	v_ashrrev_i32_e32 v21, 31, v20
	v_lshlrev_b64 v[20:21], 8, v[20:21]
	v_lshl_add_u64 v[20:21], v[20:21], 0, s[4:5]
	v_lshlrev_b64 v[20:21], 1, v[20:21]
	v_lshl_add_u64 v[22:23], v[16:17], 0, v[20:21]
	v_lshl_add_u64 v[20:21], v[18:19], 0, v[20:21]
	global_load_dwordx4 v[122:125], v[22:23], off
	global_load_dwordx4 v[126:129], v[20:21], off
	v_min_i32_e32 v20, 0x7f, v24
	v_add_u32_e32 v20, s7, v20
	v_ashrrev_i32_e32 v21, 31, v20
	v_lshlrev_b64 v[20:21], 8, v[20:21]
	v_lshl_add_u64 v[20:21], v[20:21], 0, s[4:5]
	v_lshlrev_b64 v[20:21], 1, v[20:21]
	v_lshl_add_u64 v[22:23], v[16:17], 0, v[20:21]
	v_lshl_add_u64 v[20:21], v[18:19], 0, v[20:21]
	global_load_dwordx4 v[130:133], v[22:23], off
	global_load_dwordx4 v[134:137], v[20:21], off
	v_min_i32_e32 v20, 63, v24
	v_add3_u32 v20, v20, s7, 64
	v_ashrrev_i32_e32 v21, 31, v20
	v_lshlrev_b64 v[20:21], 8, v[20:21]
	v_lshl_add_u64 v[20:21], v[20:21], 0, s[4:5]
	v_lshlrev_b64 v[20:21], 1, v[20:21]
	v_lshl_add_u64 v[22:23], v[16:17], 0, v[20:21]
	v_lshl_add_u64 v[20:21], v[18:19], 0, v[20:21]
	global_load_dwordx4 v[138:141], v[22:23], off
	global_load_dwordx4 v[142:145], v[20:21], off
	v_min_i32_e32 v20, -1, v24
	s_addk_i32 s7, 0x80
	v_add_u32_e32 v20, s7, v20
	v_ashrrev_i32_e32 v21, 31, v20
	v_lshlrev_b64 v[20:21], 8, v[20:21]
	v_lshl_add_u64 v[20:21], v[20:21], 0, s[4:5]
	v_lshlrev_b64 v[20:21], 1, v[20:21]
	v_lshl_add_u64 v[16:17], v[16:17], 0, v[20:21]
	v_lshl_add_u64 v[18:19], v[18:19], 0, v[20:21]
	global_load_dwordx4 v[146:149], v[16:17], off
	global_load_dwordx4 v[150:153], v[18:19], off
	v_lshlrev_b32_e32 v23, 1, v217
	v_readlane_b32 s10, v251, 17
	v_or_b32_e32 v24, 1, v23
	s_mov_b32 s4, 0
	s_waitcnt vmcnt(13)
	v_lshlrev_b64 v[16:17], 1, v[182:183]
	v_readlane_b32 s11, v251, 18
	v_lshrrev_b32_e32 v25, 3, v203
	v_lshlrev_b32_e32 v26, 7, v25
	v_lshlrev_b32_e32 v27, 2, v25
	v_add_u32_e32 v27, 0x10000, v27
	v_lshrrev_b32_e32 v28, 1, v25
	v_lshrrev_b32_e32 v29, 4, v25
	v_xor_b32_e32 v28, v28, v29
	v_and_b32_e32 v28, 15, v28
	v_xor_b32_e32 v28, v28, v23
	v_mov_b32_e32 v32, v25
	v_mov_b32_e32 v33, 0
	v_lshl_add_u64 v[30:31], s[82:83], 0, v[32:33]
	v_lshlrev_b64 v[30:31], 11, v[30:31]
	v_lshl_add_u64 v[30:31], s[10:11], 0, v[30:31]
	v_mov_b32_e32 v34, s91
	v_mov_b32_e32 v35, 0
	v_lshl_add_u64 v[30:31], v[34:35], 1, v[30:31]
	v_lshl_add_u64 v[30:31], v[30:31], 0, v[16:17]
	v_mov_b32_e32 v38, 0x20000
	v_mov_b32_e32 v39, 0
	v_lshl_add_u64 v[36:37], v[30:31], 0, v[38:39]
	global_load_dwordx4 v[40:43], v[30:31], off
	global_load_dwordx4 v[44:47], v[36:37], off
	global_load_dwordx4 v[48:51], v[30:31], off offset:128
	global_load_dwordx4 v[52:55], v[36:37], off offset:128
	global_load_dwordx4 v[56:59], v[30:31], off offset:256
	global_load_dwordx4 v[60:63], v[36:37], off offset:256
	global_load_dwordx4 v[64:67], v[30:31], off offset:384
	global_load_dwordx4 v[68:71], v[36:37], off offset:384
	v_lshl_add_u32 v83, v28, 3, v26
	ds_read_b64 v[72:73], v83
	v_xor_b32_e32 v84, 1, v28
	v_lshl_add_u32 v84, v84, 3, v26
	ds_read_b64 v[74:75], v84
	ds_read_b32 v76, v27
	v_xor_b32_e32 v83, 4, v28
	v_lshl_add_u32 v83, v83, 3, v26
	ds_read_b64 v[78:79], v83 offset:8192
	v_xor_b32_e32 v84, 5, v28
	v_lshl_add_u32 v84, v84, 3, v26
	ds_read_b64 v[80:81], v84 offset:8192
	ds_read_b32 v82, v27 offset:256
	s_waitcnt lgkmcnt(3)
	v_div_scale_f32 v154, s[8:9], v76, v76, 1.0
	v_rcp_f32_e32 v155, v154
	v_lshlrev_b32_e32 v88, 16, v72
	v_and_b32_e32 v89, 0xffff0000, v72
	v_fma_f32 v156, -v154, v155, 1.0
	v_fmac_f32_e32 v155, v156, v155
	v_div_scale_f32 v156, vcc, 1.0, v76, 1.0
	v_mul_f32_e32 v157, v156, v155
	v_fma_f32 v158, -v154, v157, v156
	v_fmac_f32_e32 v157, v158, v155
	v_fma_f32 v154, -v154, v157, v156
	v_div_fmas_f32 v154, v154, v155, v157
	v_div_fixup_f32 v160, v154, v76, 1.0
	v_lshlrev_b32_e32 v90, 16, v73
	v_and_b32_e32 v91, 0xffff0000, v73
	v_lshlrev_b32_e32 v92, 16, v74
	v_and_b32_e32 v93, 0xffff0000, v74
	v_lshlrev_b32_e32 v94, 16, v75
	v_and_b32_e32 v95, 0xffff0000, v75
	v_pk_mul_f32 v[88:89], v[160:161], v[88:89] op_sel_hi:[0,1]
	v_pk_mul_f32 v[90:91], v[160:161], v[90:91] op_sel_hi:[0,1]
	v_pk_mul_f32 v[92:93], v[160:161], v[92:93] op_sel_hi:[0,1]
	v_pk_mul_f32 v[94:95], v[160:161], v[94:95] op_sel_hi:[0,1]
	s_waitcnt vmcnt(7)
; #define LAS __attribute__((address_space(3)))
; __device__ __forceinline__ unsigned pkbf(float lo, float hi) { f32x2v v = {lo, hi}; return __builtin_bit_cast(unsigned, __builtin_convertvector(v, bf2_t)); }
; __device__ __forceinline__ float bflo(unsigned w) { return __uint_as_float(w << 16); }
; __device__ __forceinline__ float bfhi(unsigned w) { return __uint_as_float(w & 0xffff0000u); }
; template <int MIX, bool DRY = false>
; __device__ __forceinline__ void attn_phase(LAS unsigned char* lds, const bf16_t* Qb, const bf16_t* Kb, const bf16_t* Vb, bf16_t* Gb, const float* qg, const float* kg, const float* sinks) {
;     ...
;                 const LAS unsigned char* orow = Oacc + row * 128;
;                 const u32x2 o0 = *(const LAS u32x2*)(orow + (((2 * dg) ^ f) << 3)), o1 = *(const LAS u32x2*)(orow + (((2 * dg + 1) ^ f) << 3));
;                 const float inv = 1.0f / lacc[row];
;                 u32x4* gp = (u32x4*)(Gb + (rowb + t0 + tl) * 1024 + head * 64 + 8 * dg);
;                 const u32x4 gv = *gp;
;                 u32x4 w;
;                 w.x = pkbf(bflo(o0.x) * inv * bflo(gv.x), bfhi(o0.x) * inv * bfhi(gv.x)); w.y = pkbf(bflo(o0.y) * inv * bflo(gv.y), bfhi(o0.y) * inv * bfhi(gv.y));
;                 w.z = pkbf(bflo(o1.x) * inv * bflo(gv.z), bfhi(o1.x) * inv * bfhi(gv.z)); w.w = pkbf(bflo(o1.y) * inv * bflo(gv.w), bfhi(o1.y) * inv * bfhi(gv.w));
;                 *gp = w;
	v_lshlrev_b32_e32 v96, 16, v40
	v_and_b32_e32 v97, 0xffff0000, v40
	v_pk_mul_f32 v[88:89], v[88:89], v[96:97]
	v_lshlrev_b32_e32 v96, 16, v41
	v_and_b32_e32 v97, 0xffff0000, v41
	v_pk_mul_f32 v[90:91], v[90:91], v[96:97]
	v_lshlrev_b32_e32 v96, 16, v42
	v_and_b32_e32 v97, 0xffff0000, v42
	v_pk_mul_f32 v[92:93], v[92:93], v[96:97]
	v_lshlrev_b32_e32 v96, 16, v43
	v_and_b32_e32 v97, 0xffff0000, v43
	v_pk_mul_f32 v[94:95], v[94:95], v[96:97]
	v_cvt_pk_bf16_f32 v100, v88, v89
	v_cvt_pk_bf16_f32 v101, v90, v91
	v_cvt_pk_bf16_f32 v102, v92, v93
	v_cvt_pk_bf16_f32 v103, v94, v95
	global_store_dwordx4 v[30:31], v[100:103], off
	v_xor_b32_e32 v83, 4, v28
	v_lshl_add_u32 v83, v83, 3, v26
	ds_read_b64 v[72:73], v83 offset:16384
	v_xor_b32_e32 v84, 5, v28
	v_lshl_add_u32 v84, v84, 3, v26
	ds_read_b64 v[74:75], v84 offset:16384
	ds_read_b32 v76, v27 offset:512
	s_waitcnt lgkmcnt(3)
	v_div_scale_f32 v154, s[8:9], v82, v82, 1.0
	v_rcp_f32_e32 v155, v154
	v_lshlrev_b32_e32 v88, 16, v78
	v_and_b32_e32 v89, 0xffff0000, v78
	v_fma_f32 v156, -v154, v155, 1.0
	v_fmac_f32_e32 v155, v156, v155
	v_div_scale_f32 v156, vcc, 1.0, v82, 1.0
	v_mul_f32_e32 v157, v156, v155
	v_fma_f32 v158, -v154, v157, v156
	v_fmac_f32_e32 v157, v158, v155
	v_fma_f32 v154, -v154, v157, v156
	v_div_fmas_f32 v154, v154, v155, v157
	v_div_fixup_f32 v160, v154, v82, 1.0
	v_lshlrev_b32_e32 v90, 16, v79
	v_and_b32_e32 v91, 0xffff0000, v79
	v_lshlrev_b32_e32 v92, 16, v80
	v_and_b32_e32 v93, 0xffff0000, v80
	v_lshlrev_b32_e32 v94, 16, v81
	v_and_b32_e32 v95, 0xffff0000, v81
	v_pk_mul_f32 v[88:89], v[160:161], v[88:89] op_sel_hi:[0,1]
	v_pk_mul_f32 v[90:91], v[160:161], v[90:91] op_sel_hi:[0,1]
	v_pk_mul_f32 v[92:93], v[160:161], v[92:93] op_sel_hi:[0,1]
	v_pk_mul_f32 v[94:95], v[160:161], v[94:95] op_sel_hi:[0,1]
	s_waitcnt vmcnt(7)
	v_lshlrev_b32_e32 v96, 16, v44
	v_and_b32_e32 v97, 0xffff0000, v44
	v_pk_mul_f32 v[88:89], v[88:89], v[96:97]
	v_lshlrev_b32_e32 v96, 16, v45
	v_and_b32_e32 v97, 0xffff0000, v45
	v_pk_mul_f32 v[90:91], v[90:91], v[96:97]
	v_lshlrev_b32_e32 v96, 16, v46
	v_and_b32_e32 v97, 0xffff0000, v46
	v_pk_mul_f32 v[92:93], v[92:93], v[96:97]
	v_lshlrev_b32_e32 v96, 16, v47
	v_and_b32_e32 v97, 0xffff0000, v47
	v_pk_mul_f32 v[94:95], v[94:95], v[96:97]
	v_cvt_pk_bf16_f32 v104, v88, v89
	v_cvt_pk_bf16_f32 v105, v90, v91
	v_cvt_pk_bf16_f32 v106, v92, v93
	v_cvt_pk_bf16_f32 v107, v94, v95
	global_store_dwordx4 v[36:37], v[104:107], off
	v_lshl_add_u32 v83, v28, 3, v26
	ds_read_b64 v[78:79], v83 offset:24576
	v_xor_b32_e32 v84, 1, v28
	v_lshl_add_u32 v84, v84, 3, v26
	ds_read_b64 v[80:81], v84 offset:24576
	ds_read_b32 v82, v27 offset:768
	s_waitcnt lgkmcnt(3)
	v_div_scale_f32 v154, s[8:9], v76, v76, 1.0
	v_rcp_f32_e32 v155, v154
	v_lshlrev_b32_e32 v88, 16, v72
	v_and_b32_e32 v89, 0xffff0000, v72
	v_fma_f32 v156, -v154, v155, 1.0
	v_fmac_f32_e32 v155, v156, v155
	v_div_scale_f32 v156, vcc, 1.0, v76, 1.0
	v_mul_f32_e32 v157, v156, v155
	v_fma_f32 v158, -v154, v157, v156
	v_fmac_f32_e32 v157, v158, v155
	v_fma_f32 v154, -v154, v157, v156
	v_div_fmas_f32 v154, v154, v155, v157
	v_div_fixup_f32 v160, v154, v76, 1.0
	v_lshlrev_b32_e32 v90, 16, v73
	v_and_b32_e32 v91, 0xffff0000, v73
	v_lshlrev_b32_e32 v92, 16, v74
	v_and_b32_e32 v93, 0xffff0000, v74
	v_lshlrev_b32_e32 v94, 16, v75
	v_and_b32_e32 v95, 0xffff0000, v75
	v_pk_mul_f32 v[88:89], v[160:161], v[88:89] op_sel_hi:[0,1]
	v_pk_mul_f32 v[90:91], v[160:161], v[90:91] op_sel_hi:[0,1]
	v_pk_mul_f32 v[92:93], v[160:161], v[92:93] op_sel_hi:[0,1]
	v_pk_mul_f32 v[94:95], v[160:161], v[94:95] op_sel_hi:[0,1]
	s_waitcnt vmcnt(7)
	v_lshlrev_b32_e32 v96, 16, v48
	v_and_b32_e32 v97, 0xffff0000, v48
	v_pk_mul_f32 v[88:89], v[88:89], v[96:97]
	v_lshlrev_b32_e32 v96, 16, v49
	v_and_b32_e32 v97, 0xffff0000, v49
	v_pk_mul_f32 v[90:91], v[90:91], v[96:97]
	v_lshlrev_b32_e32 v96, 16, v50
	v_and_b32_e32 v97, 0xffff0000, v50
	v_pk_mul_f32 v[92:93], v[92:93], v[96:97]
	v_lshlrev_b32_e32 v96, 16, v51
	v_and_b32_e32 v97, 0xffff0000, v51
	v_pk_mul_f32 v[94:95], v[94:95], v[96:97]
	v_cvt_pk_bf16_f32 v100, v88, v89
	v_cvt_pk_bf16_f32 v101, v90, v91
	v_cvt_pk_bf16_f32 v102, v92, v93
	v_cvt_pk_bf16_f32 v103, v94, v95
	global_store_dwordx4 v[30:31], v[100:103], off offset:128
	v_xor_b32_e32 v83, 8, v28
	v_lshl_add_u32 v83, v83, 3, v26
	ds_read_b64 v[72:73], v83 offset:32768
	v_xor_b32_e32 v84, 9, v28
	v_lshl_add_u32 v84, v84, 3, v26
	ds_read_b64 v[74:75], v84 offset:32768
	ds_read_b32 v76, v27 offset:1024
	s_waitcnt lgkmcnt(3)
	v_div_scale_f32 v154, s[8:9], v82, v82, 1.0
	v_rcp_f32_e32 v155, v154
	v_lshlrev_b32_e32 v88, 16, v78
	v_and_b32_e32 v89, 0xffff0000, v78
	v_fma_f32 v156, -v154, v155, 1.0
	v_fmac_f32_e32 v155, v156, v155
	v_div_scale_f32 v156, vcc, 1.0, v82, 1.0
	v_mul_f32_e32 v157, v156, v155
	v_fma_f32 v158, -v154, v157, v156
	v_fmac_f32_e32 v157, v158, v155
	v_fma_f32 v154, -v154, v157, v156
	v_div_fmas_f32 v154, v154, v155, v157
	v_div_fixup_f32 v160, v154, v82, 1.0
	v_lshlrev_b32_e32 v90, 16, v79
	v_and_b32_e32 v91, 0xffff0000, v79
	v_lshlrev_b32_e32 v92, 16, v80
	v_and_b32_e32 v93, 0xffff0000, v80
	v_lshlrev_b32_e32 v94, 16, v81
	v_and_b32_e32 v95, 0xffff0000, v81
	v_pk_mul_f32 v[88:89], v[160:161], v[88:89] op_sel_hi:[0,1]
	v_pk_mul_f32 v[90:91], v[160:161], v[90:91] op_sel_hi:[0,1]
	v_pk_mul_f32 v[92:93], v[160:161], v[92:93] op_sel_hi:[0,1]
	v_pk_mul_f32 v[94:95], v[160:161], v[94:95] op_sel_hi:[0,1]
	s_waitcnt vmcnt(7)
; #define LAS __attribute__((address_space(3)))
; __device__ __forceinline__ unsigned pkbf(float lo, float hi) { f32x2v v = {lo, hi}; return __builtin_bit_cast(unsigned, __builtin_convertvector(v, bf2_t)); }
; __device__ __forceinline__ float bflo(unsigned w) { return __uint_as_float(w << 16); }
; __device__ __forceinline__ float bfhi(unsigned w) { return __uint_as_float(w & 0xffff0000u); }
; template <int MIX, bool DRY = false>
; __device__ __forceinline__ void attn_phase(LAS unsigned char* lds, const bf16_t* Qb, const bf16_t* Kb, const bf16_t* Vb, bf16_t* Gb, const float* qg, const float* kg, const float* sinks) {
;     ...
;                 const LAS unsigned char* orow = Oacc + row * 128;
;                 const u32x2 o0 = *(const LAS u32x2*)(orow + (((2 * dg) ^ f) << 3)), o1 = *(const LAS u32x2*)(orow + (((2 * dg + 1) ^ f) << 3));
;                 const float inv = 1.0f / lacc[row];
;                 u32x4* gp = (u32x4*)(Gb + (rowb + t0 + tl) * 1024 + head * 64 + 8 * dg);
;                 const u32x4 gv = *gp;
;                 u32x4 w;
;                 w.x = pkbf(bflo(o0.x) * inv * bflo(gv.x), bfhi(o0.x) * inv * bfhi(gv.x)); w.y = pkbf(bflo(o0.y) * inv * bflo(gv.y), bfhi(o0.y) * inv * bfhi(gv.y));
;                 w.z = pkbf(bflo(o1.x) * inv * bflo(gv.z), bfhi(o1.x) * inv * bfhi(gv.z)); w.w = pkbf(bflo(o1.y) * inv * bflo(gv.w), bfhi(o1.y) * inv * bfhi(gv.w));
;                 *gp = w;
	v_lshlrev_b32_e32 v96, 16, v52
	v_and_b32_e32 v97, 0xffff0000, v52
	v_pk_mul_f32 v[88:89], v[88:89], v[96:97]
	v_lshlrev_b32_e32 v96, 16, v53
	v_and_b32_e32 v97, 0xffff0000, v53
	v_pk_mul_f32 v[90:91], v[90:91], v[96:97]
	v_lshlrev_b32_e32 v96, 16, v54
	v_and_b32_e32 v97, 0xffff0000, v54
	v_pk_mul_f32 v[92:93], v[92:93], v[96:97]
	v_lshlrev_b32_e32 v96, 16, v55
	v_and_b32_e32 v97, 0xffff0000, v55
	v_pk_mul_f32 v[94:95], v[94:95], v[96:97]
	v_cvt_pk_bf16_f32 v104, v88, v89
	v_cvt_pk_bf16_f32 v105, v90, v91
	v_cvt_pk_bf16_f32 v106, v92, v93
	v_cvt_pk_bf16_f32 v107, v94, v95
	global_store_dwordx4 v[36:37], v[104:107], off offset:128
	v_xor_b32_e32 v83, 12, v28
	v_lshl_add_u32 v83, v83, 3, v26
	ds_read_b64 v[78:79], v83 offset:40960
	v_xor_b32_e32 v84, 13, v28
	v_lshl_add_u32 v84, v84, 3, v26
	ds_read_b64 v[80:81], v84 offset:40960
	ds_read_b32 v82, v27 offset:1280
	s_waitcnt lgkmcnt(3)
	v_div_scale_f32 v154, s[8:9], v76, v76, 1.0
	v_rcp_f32_e32 v155, v154
	v_lshlrev_b32_e32 v88, 16, v72
	v_and_b32_e32 v89, 0xffff0000, v72
	v_fma_f32 v156, -v154, v155, 1.0
	v_fmac_f32_e32 v155, v156, v155
	v_div_scale_f32 v156, vcc, 1.0, v76, 1.0
	v_mul_f32_e32 v157, v156, v155
	v_fma_f32 v158, -v154, v157, v156
	v_fmac_f32_e32 v157, v158, v155
	v_fma_f32 v154, -v154, v157, v156
	v_div_fmas_f32 v154, v154, v155, v157
	v_div_fixup_f32 v160, v154, v76, 1.0
	v_lshlrev_b32_e32 v90, 16, v73
	v_and_b32_e32 v91, 0xffff0000, v73
	v_lshlrev_b32_e32 v92, 16, v74
	v_and_b32_e32 v93, 0xffff0000, v74
	v_lshlrev_b32_e32 v94, 16, v75
	v_and_b32_e32 v95, 0xffff0000, v75
	v_pk_mul_f32 v[88:89], v[160:161], v[88:89] op_sel_hi:[0,1]
	v_pk_mul_f32 v[90:91], v[160:161], v[90:91] op_sel_hi:[0,1]
	v_pk_mul_f32 v[92:93], v[160:161], v[92:93] op_sel_hi:[0,1]
	v_pk_mul_f32 v[94:95], v[160:161], v[94:95] op_sel_hi:[0,1]
	s_waitcnt vmcnt(7)
	v_lshlrev_b32_e32 v96, 16, v56
	v_and_b32_e32 v97, 0xffff0000, v56
	v_pk_mul_f32 v[88:89], v[88:89], v[96:97]
	v_lshlrev_b32_e32 v96, 16, v57
	v_and_b32_e32 v97, 0xffff0000, v57
	v_pk_mul_f32 v[90:91], v[90:91], v[96:97]
	v_lshlrev_b32_e32 v96, 16, v58
	v_and_b32_e32 v97, 0xffff0000, v58
	v_pk_mul_f32 v[92:93], v[92:93], v[96:97]
	v_lshlrev_b32_e32 v96, 16, v59
	v_and_b32_e32 v97, 0xffff0000, v59
	v_pk_mul_f32 v[94:95], v[94:95], v[96:97]
	v_cvt_pk_bf16_f32 v100, v88, v89
	v_cvt_pk_bf16_f32 v101, v90, v91
	v_cvt_pk_bf16_f32 v102, v92, v93
	v_cvt_pk_bf16_f32 v103, v94, v95
	global_store_dwordx4 v[30:31], v[100:103], off offset:256
	v_xor_b32_e32 v83, 12, v28
	v_lshl_add_u32 v83, v83, 3, v26
	ds_read_b64 v[72:73], v83 offset:49152
	v_xor_b32_e32 v84, 13, v28
	v_lshl_add_u32 v84, v84, 3, v26
	ds_read_b64 v[74:75], v84 offset:49152
	ds_read_b32 v76, v27 offset:1536
	s_waitcnt lgkmcnt(3)
	v_div_scale_f32 v154, s[8:9], v82, v82, 1.0
	v_rcp_f32_e32 v155, v154
	v_lshlrev_b32_e32 v88, 16, v78
	v_and_b32_e32 v89, 0xffff0000, v78
	v_fma_f32 v156, -v154, v155, 1.0
	v_fmac_f32_e32 v155, v156, v155
	v_div_scale_f32 v156, vcc, 1.0, v82, 1.0
	v_mul_f32_e32 v157, v156, v155
	v_fma_f32 v158, -v154, v157, v156
	v_fmac_f32_e32 v157, v158, v155
	v_fma_f32 v154, -v154, v157, v156
	v_div_fmas_f32 v154, v154, v155, v157
	v_div_fixup_f32 v160, v154, v82, 1.0
	v_lshlrev_b32_e32 v90, 16, v79
	v_and_b32_e32 v91, 0xffff0000, v79
	v_lshlrev_b32_e32 v92, 16, v80
	v_and_b32_e32 v93, 0xffff0000, v80
	v_lshlrev_b32_e32 v94, 16, v81
	v_and_b32_e32 v95, 0xffff0000, v81
	v_pk_mul_f32 v[88:89], v[160:161], v[88:89] op_sel_hi:[0,1]
	v_pk_mul_f32 v[90:91], v[160:161], v[90:91] op_sel_hi:[0,1]
	v_pk_mul_f32 v[92:93], v[160:161], v[92:93] op_sel_hi:[0,1]
	v_pk_mul_f32 v[94:95], v[160:161], v[94:95] op_sel_hi:[0,1]
	s_waitcnt vmcnt(7)
	v_lshlrev_b32_e32 v96, 16, v60
	v_and_b32_e32 v97, 0xffff0000, v60
	v_pk_mul_f32 v[88:89], v[88:89], v[96:97]
	v_lshlrev_b32_e32 v96, 16, v61
	v_and_b32_e32 v97, 0xffff0000, v61
	v_pk_mul_f32 v[90:91], v[90:91], v[96:97]
	v_lshlrev_b32_e32 v96, 16, v62
	v_and_b32_e32 v97, 0xffff0000, v62
	v_pk_mul_f32 v[92:93], v[92:93], v[96:97]
	v_lshlrev_b32_e32 v96, 16, v63
	v_and_b32_e32 v97, 0xffff0000, v63
	v_pk_mul_f32 v[94:95], v[94:95], v[96:97]
	v_cvt_pk_bf16_f32 v104, v88, v89
	v_cvt_pk_bf16_f32 v105, v90, v91
	v_cvt_pk_bf16_f32 v106, v92, v93
	v_cvt_pk_bf16_f32 v107, v94, v95
	global_store_dwordx4 v[36:37], v[104:107], off offset:256
	v_xor_b32_e32 v83, 8, v28
	v_lshl_add_u32 v83, v83, 3, v26
	ds_read_b64 v[78:79], v83 offset:57344
	v_xor_b32_e32 v84, 9, v28
	v_lshl_add_u32 v84, v84, 3, v26
	ds_read_b64 v[80:81], v84 offset:57344
	ds_read_b32 v82, v27 offset:1792
	s_waitcnt lgkmcnt(3)
; #define LAS __attribute__((address_space(3)))
; __device__ __forceinline__ unsigned pkbf(float lo, float hi) { f32x2v v = {lo, hi}; return __builtin_bit_cast(unsigned, __builtin_convertvector(v, bf2_t)); }
; __device__ __forceinline__ float bflo(unsigned w) { return __uint_as_float(w << 16); }
; __device__ __forceinline__ float bfhi(unsigned w) { return __uint_as_float(w & 0xffff0000u); }
; template <int MIX, bool DRY = false>
; __device__ __forceinline__ void attn_phase(LAS unsigned char* lds, const bf16_t* Qb, const bf16_t* Kb, const bf16_t* Vb, bf16_t* Gb, const float* qg, const float* kg, const float* sinks) {
;     ...
;                 const LAS unsigned char* orow = Oacc + row * 128;
;                 const u32x2 o0 = *(const LAS u32x2*)(orow + (((2 * dg) ^ f) << 3)), o1 = *(const LAS u32x2*)(orow + (((2 * dg + 1) ^ f) << 3));
;                 const float inv = 1.0f / lacc[row];
;                 u32x4* gp = (u32x4*)(Gb + (rowb + t0 + tl) * 1024 + head * 64 + 8 * dg);
;                 const u32x4 gv = *gp;
;                 u32x4 w;
;                 w.x = pkbf(bflo(o0.x) * inv * bflo(gv.x), bfhi(o0.x) * inv * bfhi(gv.x)); w.y = pkbf(bflo(o0.y) * inv * bflo(gv.y), bfhi(o0.y) * inv * bfhi(gv.y));
;                 w.z = pkbf(bflo(o1.x) * inv * bflo(gv.z), bfhi(o1.x) * inv * bfhi(gv.z)); w.w = pkbf(bflo(o1.y) * inv * bflo(gv.w), bfhi(o1.y) * inv * bfhi(gv.w));
;                 *gp = w;
;             }
;             if (more) STAGE_STORE(0)
	v_div_scale_f32 v154, s[8:9], v76, v76, 1.0
	v_rcp_f32_e32 v155, v154
	v_lshlrev_b32_e32 v88, 16, v72
	v_and_b32_e32 v89, 0xffff0000, v72
	v_fma_f32 v156, -v154, v155, 1.0
	v_fmac_f32_e32 v155, v156, v155
	v_div_scale_f32 v156, vcc, 1.0, v76, 1.0
	v_mul_f32_e32 v157, v156, v155
	v_fma_f32 v158, -v154, v157, v156
	v_fmac_f32_e32 v157, v158, v155
	v_fma_f32 v154, -v154, v157, v156
	v_div_fmas_f32 v154, v154, v155, v157
	v_div_fixup_f32 v160, v154, v76, 1.0
	v_lshlrev_b32_e32 v90, 16, v73
	v_and_b32_e32 v91, 0xffff0000, v73
	v_lshlrev_b32_e32 v92, 16, v74
	v_and_b32_e32 v93, 0xffff0000, v74
	v_lshlrev_b32_e32 v94, 16, v75
	v_and_b32_e32 v95, 0xffff0000, v75
	v_pk_mul_f32 v[88:89], v[160:161], v[88:89] op_sel_hi:[0,1]
	v_pk_mul_f32 v[90:91], v[160:161], v[90:91] op_sel_hi:[0,1]
	v_pk_mul_f32 v[92:93], v[160:161], v[92:93] op_sel_hi:[0,1]
	v_pk_mul_f32 v[94:95], v[160:161], v[94:95] op_sel_hi:[0,1]
	s_waitcnt vmcnt(7)
	v_lshlrev_b32_e32 v96, 16, v64
	v_and_b32_e32 v97, 0xffff0000, v64
	v_pk_mul_f32 v[88:89], v[88:89], v[96:97]
	v_lshlrev_b32_e32 v96, 16, v65
	v_and_b32_e32 v97, 0xffff0000, v65
	v_pk_mul_f32 v[90:91], v[90:91], v[96:97]
	v_lshlrev_b32_e32 v96, 16, v66
	v_and_b32_e32 v97, 0xffff0000, v66
	v_pk_mul_f32 v[92:93], v[92:93], v[96:97]
	v_lshlrev_b32_e32 v96, 16, v67
	v_and_b32_e32 v97, 0xffff0000, v67
	v_pk_mul_f32 v[94:95], v[94:95], v[96:97]
	v_cvt_pk_bf16_f32 v100, v88, v89
	v_cvt_pk_bf16_f32 v101, v90, v91
	v_cvt_pk_bf16_f32 v102, v92, v93
	v_cvt_pk_bf16_f32 v103, v94, v95
	global_store_dwordx4 v[30:31], v[100:103], off offset:384
	s_waitcnt lgkmcnt(0)
	v_div_scale_f32 v154, s[8:9], v82, v82, 1.0
	v_rcp_f32_e32 v155, v154
	v_lshlrev_b32_e32 v88, 16, v78
	v_and_b32_e32 v89, 0xffff0000, v78
	v_fma_f32 v156, -v154, v155, 1.0
	v_fmac_f32_e32 v155, v156, v155
	v_div_scale_f32 v156, vcc, 1.0, v82, 1.0
	v_mul_f32_e32 v157, v156, v155
	v_fma_f32 v158, -v154, v157, v156
	v_fmac_f32_e32 v157, v158, v155
	v_fma_f32 v154, -v154, v157, v156
	v_div_fmas_f32 v154, v154, v155, v157
	v_div_fixup_f32 v160, v154, v82, 1.0
	v_lshlrev_b32_e32 v90, 16, v79
	v_and_b32_e32 v91, 0xffff0000, v79
	v_lshlrev_b32_e32 v92, 16, v80
	v_and_b32_e32 v93, 0xffff0000, v80
	v_lshlrev_b32_e32 v94, 16, v81
	v_and_b32_e32 v95, 0xffff0000, v81
	v_pk_mul_f32 v[88:89], v[160:161], v[88:89] op_sel_hi:[0,1]
	v_pk_mul_f32 v[90:91], v[160:161], v[90:91] op_sel_hi:[0,1]
	v_pk_mul_f32 v[92:93], v[160:161], v[92:93] op_sel_hi:[0,1]
	v_pk_mul_f32 v[94:95], v[160:161], v[94:95] op_sel_hi:[0,1]
	s_waitcnt vmcnt(7)
	v_lshlrev_b32_e32 v96, 16, v68
	v_and_b32_e32 v97, 0xffff0000, v68
	v_pk_mul_f32 v[88:89], v[88:89], v[96:97]
	v_lshlrev_b32_e32 v96, 16, v69
	v_and_b32_e32 v97, 0xffff0000, v69
	v_pk_mul_f32 v[90:91], v[90:91], v[96:97]
	v_lshlrev_b32_e32 v96, 16, v70
	v_and_b32_e32 v97, 0xffff0000, v70
	v_pk_mul_f32 v[92:93], v[92:93], v[96:97]
	v_lshlrev_b32_e32 v96, 16, v71
	v_and_b32_e32 v97, 0xffff0000, v71
	v_pk_mul_f32 v[94:95], v[94:95], v[96:97]
	v_cvt_pk_bf16_f32 v104, v88, v89
	v_cvt_pk_bf16_f32 v105, v90, v91
	v_cvt_pk_bf16_f32 v106, v92, v93
	v_cvt_pk_bf16_f32 v107, v94, v95
	global_store_dwordx4 v[36:37], v[104:107], off offset:384
	v_readlane_b32 s82, v251, 47
	s_mov_b64 s[4:5], -1
	s_and_b64 vcc, exec, s[0:1]
	v_readlane_b32 s83, v251, 48
	v_readlane_b32 s91, v251, 49
	s_cbranch_vccz .LBB0_407
	v_mov_b32_e32 v16, v202
	s_movk_i32 s0, 0x100
	v_ashrrev_i32_e32 v17, 3, v16
	v_cmp_gt_i32_e32 vcc, s0, v17
	s_and_saveexec_b64 s[0:1], vcc
	s_cbranch_execz .LBB0_474
	v_ashrrev_i32_e32 v19, 4, v16
	v_lshlrev_b32_e32 v20, 2, v19
	v_and_b32_e32 v20, 4, v20
	v_xor_b32_e32 v19, v19, v16
	v_lshlrev_b32_e32 v18, 7, v17
	v_bitop3_b32 v19, v19, v20, 7 bitop3:0x6c
	v_lshl_or_b32 v18, v19, 4, v18
	v_add_u32_e32 v18, 0, v18
	v_add_u32_e32 v19, 0x10800, v18
	v_add_u32_e32 v18, 0x1a800, v18
	ds_write_b128 v19, v[114:117]
	ds_write_b128 v18, v[118:121]
